# v10
# speedup vs baseline: 1.0028x; 1.0028x over previous
.LBB0_1498:
	v_mbcnt_lo_u32_b32 v5, -1, 0
	v_mbcnt_hi_u32_b32 v5, -1, v5
	v_readlane_b32 s1, v252, 54
	v_lshl_or_b32 v0, s83, 6, v5
	v_readlane_b32 s3, v254, 26
	v_readfirstlane_b32 s0, v0
	s_ashr_i32 s0, s0, 6
	s_add_i32 s2, s0, s1
	v_readlane_b32 s0, v252, 57
	s_sub_i32 s0, s0, s2
	s_ashr_i32 s1, s0, 31
	s_xor_b32 s1, s1, s3
	s_abs_i32 s0, s0
	v_readlane_b32 s3, v253, 56
	s_mul_hi_u32 s3, s0, s3
	v_readlane_b32 s6, v253, 55
	s_mul_i32 s4, s3, s6
	s_sub_i32 s0, s0, s4
	s_add_i32 s4, s3, 1
	s_sub_i32 s5, s0, s6
	s_cmp_ge_u32 s0, s6
	s_cselect_b32 s3, s4, s3
	s_cselect_b32 s0, s5, s0
	s_add_i32 s4, s3, 1
	s_cmp_ge_u32 s0, s6
	s_cselect_b32 s0, s4, s3
	s_xor_b32 s0, s0, s1
	s_sub_i32 s8, s0, s1
	s_cmp_lt_i32 s8, 1
	s_cbranch_scc1 .LBB0_1504
	v_readlane_b32 s12, v252, 37
	v_readlane_b32 s13, v252, 38
	v_readlane_b32 s14, v252, 39
	v_readlane_b32 s15, v252, 40
	v_readlane_b32 s24, v252, 49
	v_readlane_b32 s25, v252, 50
	s_ashr_i32 s3, s2, 31
	v_readlane_b32 s26, v252, 51
	v_readlane_b32 s27, v252, 52
	s_mov_b64 s[12:13], s[24:25]
	s_lshl_b64 s[0:1], s[2:3], 13
	s_mov_b64 s[14:15], s[26:27]
	v_lshlrev_b32_e32 v0, 4, v5
	s_add_u32 s0, s14, s0
	v_and_b32_e32 v6, 0x3f0, v0
	s_addc_u32 s1, s15, s1
	v_or_b32_e32 v36, 0x1c00, v6
	v_or_b32_e32 v40, 0x1400, v6
	v_or_b32_e32 v38, 0x1800, v6
	global_load_dwordx4 v[0:3], v36, s[0:1]
	global_load_dwordx4 v[8:11], v38, s[0:1]
	v_or_b32_e32 v42, 0x1000, v6
	global_load_dwordx4 v[12:15], v40, s[0:1]
	global_load_dwordx4 v[16:19], v42, s[0:1]
	global_load_dwordx4 v[20:23], v6, s[0:1] offset:3072
	global_load_dwordx4 v[24:27], v6, s[0:1] offset:2048
	global_load_dwordx4 v[28:31], v6, s[0:1] offset:1024
	global_load_dwordx4 v[32:35], v6, s[0:1]
	v_xor_b32_e32 v44, 32, v202
	v_cmp_lt_i32_e32 vcc, v44, v203
	v_readlane_b32 s10, v254, 36
	s_add_i32 s2, s2, s10
	v_cndmask_b32_e32 v44, v202, v44, vcc
	v_cmp_lt_i32_e32 vcc, v208, v203
	v_lshlrev_b32_e32 v80, 2, v44
	s_ashr_i32 s3, s2, 31
	v_cndmask_b32_e32 v44, v202, v208, vcc
	v_cmp_lt_i32_e32 vcc, v211, v203
	v_lshlrev_b32_e32 v81, 2, v44
	v_mov_b32_e32 v4, 0
	v_cndmask_b32_e32 v44, v202, v211, vcc
	v_cmp_lt_i32_e32 vcc, v222, v203
	v_lshlrev_b32_e32 v82, 2, v44
	s_lshl_b64 s[4:5], s[2:3], 13
	v_cndmask_b32_e32 v44, v202, v222, vcc
	v_cmp_lt_i32_e32 vcc, v209, v203
	v_lshlrev_b32_e32 v83, 2, v44
	v_mov_b32_e32 v37, v4
	v_cndmask_b32_e32 v44, v202, v209, vcc
	v_cmp_lt_i32_e32 vcc, v251, v203
	v_mov_b32_e32 v39, v4
	v_mov_b32_e32 v41, v4
	v_mov_b32_e32 v43, v4
	v_mov_b32_e32 v7, v4
	v_lshlrev_b32_e32 v84, 2, v44
	v_cndmask_b32_e32 v44, v202, v251, vcc
	v_readlane_b32 s11, v254, 37
	v_and_b32_e32 v5, 63, v5
	s_add_u32 s4, s14, s4
	s_movk_i32 s9, 0x1000
	v_lshlrev_b32_e32 v85, 2, v44
	v_lshl_add_u64 v[68:69], s[12:13], 0, v[6:7]
	v_lshl_add_u64 v[70:71], s[12:13], 0, v[42:43]
	v_lshl_add_u64 v[72:73], s[12:13], 0, v[40:41]
	v_lshl_add_u64 v[74:75], s[12:13], 0, v[38:39]
	v_lshl_add_u64 v[76:77], s[12:13], 0, v[36:37]
	v_lshlrev_b32_e32 v78, 4, v5
	v_mov_b32_e32 v79, v4
	s_addc_u32 s5, s15, s5
	s_lshl_b64 s[6:7], s[10:11], 13
	v_mov_b32_e32 v86, 0x358637bd
	s_mov_b32 s3, 0x800000
	v_readlane_b32 s16, v252, 41
	v_readlane_b32 s17, v252, 42
	v_readlane_b32 s18, v252, 43
	v_readlane_b32 s19, v252, 44
	v_readlane_b32 s20, v252, 45
	v_readlane_b32 s21, v252, 46
	v_readlane_b32 s22, v252, 47
	v_readlane_b32 s23, v252, 48
	global_load_dwordx4 v[96:99], v[68:69], off
	global_load_dwordx4 v[100:103], v[68:69], off offset:1024
	global_load_dwordx4 v[104:107], v[68:69], off offset:2048
	global_load_dwordx4 v[108:111], v[68:69], off offset:3072
	global_load_dwordx4 v[112:115], v[70:71], off
	global_load_dwordx4 v[116:119], v[72:73], off
	global_load_dwordx4 v[120:123], v[74:75], off
	global_load_dwordx4 v[124:127], v[76:77], off
	s_waitcnt vmcnt(0)
	s_branch .LBB0_1502

.LBB0_1501:
	s_waitcnt vmcnt(0)
	v_mul_f32_e32 v5, v33, v33
	v_mul_f32_e32 v6, v29, v29
	v_fmac_f32_e32 v5, v32, v32
	v_fmac_f32_e32 v6, v28, v28
	v_fmac_f32_e32 v5, v34, v34
	v_fmac_f32_e32 v6, v30, v30
	v_fmac_f32_e32 v5, v35, v35
	v_fmac_f32_e32 v6, v31, v31
	v_add_f32_e32 v5, v6, v5
	v_mul_f32_e32 v6, v25, v25
	v_fmac_f32_e32 v6, v24, v24
	v_fmac_f32_e32 v6, v26, v26
	v_fmac_f32_e32 v6, v27, v27
	v_add_f32_e32 v5, v6, v5
	v_mul_f32_e32 v6, v21, v21
	v_fmac_f32_e32 v6, v20, v20
	v_fmac_f32_e32 v6, v22, v22
	v_fmac_f32_e32 v6, v23, v23
	v_mov_b32_e32 v92, v13
	v_mov_b32_e32 v93, v17
	v_add_f32_e32 v5, v6, v5
	v_mov_b32_e32 v6, v12
	v_mov_b32_e32 v7, v16
	v_pk_mul_f32 v[92:93], v[92:93], v[92:93]
	s_add_i32 s8, s8, -1
	v_pk_fma_f32 v[6:7], v[6:7], v[6:7], v[92:93]
	v_mov_b32_e32 v92, v14
	v_mov_b32_e32 v93, v18
	v_pk_fma_f32 v[6:7], v[92:93], v[92:93], v[6:7]
	v_mov_b32_e32 v92, v15
	v_mov_b32_e32 v93, v19
	v_pk_fma_f32 v[6:7], v[92:93], v[92:93], v[6:7]
	v_mov_b32_e32 v92, v1
	v_add_f32_e32 v5, v7, v5
	v_mov_b32_e32 v93, v9
	v_add_f32_e32 v5, v6, v5
	v_mov_b32_e32 v6, v0
	v_mov_b32_e32 v7, v8
	v_pk_mul_f32 v[92:93], v[92:93], v[92:93]
	s_add_i32 s2, s2, s10
	v_pk_fma_f32 v[6:7], v[6:7], v[6:7], v[92:93]
	v_mov_b32_e32 v92, v2
	v_mov_b32_e32 v93, v10
	v_pk_fma_f32 v[6:7], v[92:93], v[92:93], v[6:7]
	v_mov_b32_e32 v92, v3
	v_mov_b32_e32 v93, v11
	v_pk_fma_f32 v[6:7], v[92:93], v[92:93], v[6:7]
	s_add_u32 s4, s4, s6
	v_add_f32_e32 v5, v7, v5
	v_add_f32_e32 v5, v6, v5
	ds_bpermute_b32 v6, v80, v5
	s_addc_u32 s5, s5, s7
	s_waitcnt lgkmcnt(0)
	v_add_f32_e32 v5, v5, v6
	ds_bpermute_b32 v6, v81, v5
	s_waitcnt lgkmcnt(0)
	v_add_f32_e32 v5, v5, v6
	ds_bpermute_b32 v6, v82, v5
	s_waitcnt lgkmcnt(0)
	v_add_f32_e32 v5, v5, v6
	ds_bpermute_b32 v6, v83, v5
	s_waitcnt lgkmcnt(0)
	v_add_f32_e32 v5, v5, v6
	ds_bpermute_b32 v6, v84, v5
	s_waitcnt lgkmcnt(0)
	v_add_f32_e32 v5, v5, v6
	ds_bpermute_b32 v6, v85, v5
	s_waitcnt lgkmcnt(0)
	v_add_f32_e32 v5, v5, v6
	v_fmamk_f32 v5, v5, 0x3a000000, v86
	v_mul_f32_e32 v6, 0x4b800000, v5
	v_cmp_gt_f32_e32 vcc, s3, v5
	s_nop 1
	v_cndmask_b32_e32 v5, v5, v6, vcc
	v_rsq_f32_e32 v5, v5
	v_lshl_add_u64 v[6:7], s[0:1], 0, v[78:79]
	s_add_u32 s0, s0, s6
	s_addc_u32 s1, s1, s7
	v_mul_f32_e32 v87, 0x45800000, v5
	v_cndmask_b32_e32 v92, v5, v87, vcc
	v_pk_mul_f32 v[32:33], v[32:33], v[92:93] op_sel_hi:[1,0]
	v_pk_mul_f32 v[34:35], v[34:35], v[92:93] op_sel_hi:[1,0]
	v_pk_mul_f32 v[32:33], v[96:97], v[32:33]
	v_pk_mul_f32 v[34:35], v[98:99], v[34:35]
	global_store_dwordx4 v[6:7], v[32:35], off
	v_pk_mul_f32 v[30:31], v[30:31], v[92:93] op_sel_hi:[1,0]
	v_pk_mul_f32 v[28:29], v[28:29], v[92:93] op_sel_hi:[1,0]
	v_pk_mul_f32 v[26:27], v[26:27], v[92:93] op_sel_hi:[1,0]
	v_pk_mul_f32 v[24:25], v[24:25], v[92:93] op_sel_hi:[1,0]
	v_pk_mul_f32 v[22:23], v[22:23], v[92:93] op_sel_hi:[1,0]
	v_pk_mul_f32 v[20:21], v[20:21], v[92:93] op_sel_hi:[1,0]
	v_add_co_u32_e32 v94, vcc, s9, v6
	v_pk_mul_f32 v[16:17], v[16:17], v[92:93] op_sel_hi:[1,0]
	s_nop 0
	v_addc_co_u32_e32 v95, vcc, 0, v7, vcc
	v_pk_mul_f32 v[12:13], v[12:13], v[92:93] op_sel_hi:[1,0]
	v_pk_mul_f32 v[10:11], v[10:11], v[92:93] op_sel_hi:[1,0]
	s_cmp_lg_u32 s8, 0
	v_pk_mul_f32 v[28:29], v[100:101], v[28:29]
	v_pk_mul_f32 v[30:31], v[102:103], v[30:31]
	global_store_dwordx4 v[6:7], v[28:31], off offset:1024
	v_mov_b32_e32 v32, v36
	v_mov_b32_e32 v33, v37
	v_mov_b32_e32 v34, v38
	v_mov_b32_e32 v35, v39
	v_pk_mul_f32 v[24:25], v[104:105], v[24:25]
	v_pk_mul_f32 v[26:27], v[106:107], v[26:27]
	global_store_dwordx4 v[6:7], v[24:27], off offset:2048
	v_mov_b32_e32 v28, v40
	v_mov_b32_e32 v29, v41
	v_mov_b32_e32 v30, v42
	v_mov_b32_e32 v31, v43
	v_pk_mul_f32 v[20:21], v[108:109], v[20:21]
	v_pk_mul_f32 v[22:23], v[110:111], v[22:23]
	global_store_dwordx4 v[6:7], v[20:23], off offset:3072
	v_pk_mul_f32 v[6:7], v[18:19], v[92:93] op_sel_hi:[1,0]
	v_mov_b32_e32 v24, v44
	v_mov_b32_e32 v25, v45
	v_mov_b32_e32 v26, v46
	v_mov_b32_e32 v27, v47
	v_pk_mul_f32 v[16:17], v[112:113], v[16:17]
	v_pk_mul_f32 v[18:19], v[114:115], v[6:7]
	global_store_dwordx4 v[94:95], v[16:19], off
	v_pk_mul_f32 v[6:7], v[14:15], v[92:93] op_sel_hi:[1,0]
	v_mov_b32_e32 v20, v48
	v_mov_b32_e32 v21, v49
	v_mov_b32_e32 v22, v50
	v_mov_b32_e32 v23, v51
	v_pk_mul_f32 v[12:13], v[116:117], v[12:13]
	v_pk_mul_f32 v[14:15], v[118:119], v[6:7]
	global_store_dwordx4 v[94:95], v[12:15], off offset:1024
	v_pk_mul_f32 v[6:7], v[8:9], v[92:93] op_sel_hi:[1,0]
	v_mov_b32_e32 v16, v56
	v_mov_b32_e32 v17, v57
	v_mov_b32_e32 v18, v58
	v_mov_b32_e32 v19, v59
	v_pk_mul_f32 v[6:7], v[6:7], v[120:121]
	v_pk_mul_f32 v[8:9], v[10:11], v[122:123]
	global_store_dwordx4 v[94:95], v[6:9], off offset:2048
	v_mov_b32_e32 v10, v66
	s_nop 0
	v_pk_mul_f32 v[6:7], v[2:3], v[92:93] op_sel_hi:[1,0]
	v_pk_mul_f32 v[92:93], v[0:1], v[92:93] op_sel_hi:[1,0]
	v_mov_b64_e32 v[0:1], v[52:53]
	v_mov_b64_e32 v[2:3], v[54:55]
	v_mov_b32_e32 v8, v64
	v_mov_b32_e32 v9, v65
	v_mov_b32_e32 v11, v67
	v_mov_b32_e32 v12, v60
	v_mov_b32_e32 v13, v61
	v_mov_b32_e32 v14, v62
	v_mov_b32_e32 v15, v63
	v_pk_mul_f32 v[40:41], v[92:93], v[124:125]
	v_pk_mul_f32 v[42:43], v[6:7], v[126:127]
	global_store_dwordx4 v[94:95], v[40:43], off offset:3072
	s_cbranch_scc0 .LBB0_1504
